# plus P7b attention-sample: 16-lane xor shuffles (ds_bpermute) replaced by exact DPP register shuffles
# speedup vs baseline: 1.0008x; 1.0008x over previous
; DEV float bf2f(unsigned b) { return __uint_as_float(b << 16); }
; DEV void attn_sample_item(const Params& p, int item, unsigned char* lds) {
;     int tid = threadIdx.x & 255; asm volatile("" : "+v"(tid)); const int lane = tid & 63, wid = tid >> 6;
;     const int sb = item >> 2, hd = item & 3;
;     float* qs = (float*)lds;
;     float* pm = qs + 2048;
;     float* red = pm + 1024;
;     const bf16_t* qx = (const bf16_t*)(p.ws + WS_QX);
;     for (int i = tid; i < 2048; i += 256) { const int t = i >> 9, d = i & 511; qs[i] = bf2f(qx[(size_t)(TP + sb * 4 + t) * LDB + hd * 512 + d]) * 0.04419417382415922f; }
.LBB0_1207:
	s_mov_b64 s[52:53], 0xffffffff
	s_mov_b32 s54, 0xffff
	s_mov_b32 s55, 0xffff
	s_add_i32 s4, s31, s27
	s_min_i32 s47, s4, 0x1ff
	v_mov_b32_e32 v68, v1
	s_and_b32 s48, s47, 3
	v_cmp_lt_i32_e32 vcc, s38, v68
	s_and_saveexec_b64 s[4:5], vcc
	s_xor_b64 s[4:5], exec, s[4:5]
	s_lshl_b32 s12, s48, 9
	s_or_saveexec_b64 s[4:5], s[4:5]
	v_mov_b64_e32 v[70:71], s[12:13]
	s_xor_b64 exec, exec, s[4:5]
	s_cbranch_execz .LBB0_1222
	s_and_b32 s12, s47, -4
	v_max_i32_e32 v2, 0x700, v68
	s_addk_i32 s12, 0x2000
	s_lshl_b32 s14, s48, 10
	v_sub_u32_e32 v2, v2, v68
	s_add_u32 s18, s34, s14
	v_add_u32_e32 v2, 0xff, v2
	s_addc_u32 s19, s35, 0
	v_cmp_lt_u32_e32 vcc, s26, v2
	s_mov_b64 s[22:23], -1
	v_mov_b32_e32 v4, v68
	s_and_saveexec_b64 s[20:21], vcc
	s_cbranch_execz .LBB0_1218
	v_lshrrev_b32_e32 v6, 8, v2
	v_add_u32_e32 v69, 0x100, v68
	v_add_u32_e32 v7, -1, v6
	v_cmp_lt_u32_e32 vcc, 1, v7
	v_mov_b32_e32 v4, 0
	v_mov_b64_e32 v[2:3], v[68:69]
	s_and_saveexec_b64 s[22:23], vcc
	s_cbranch_execz .LBB0_1215
	v_lshrrev_b32_e32 v2, 1, v7
	v_add_u32_e32 v2, 1, v2
	v_and_b32_e32 v8, -2, v2
	v_lshl_add_u32 v9, v68, 2, s30
	s_mov_b32 s49, 0
	s_mov_b64 s[24:25], 0
	v_mov_b64_e32 v[4:5], s[18:19]
	v_mov_b64_e32 v[2:3], v[68:69]

; DEV void attn_sample_item(const Params& p, int item, unsigned char* lds) {
;     ...
;         for (int it = 0; it < 16; ++it) {
;             const int m = wid * 64 + it * 4 + sub;
;             f32x4 cv[8];
; #pragma unroll
;             for (int i = 0; i < 8; ++i) cv[i] = kv[i];
;             if (it + 1 < 16) {
;                 const float* kr = Kc + (size_t)(m + 4) * D;
; #pragma unroll
;                 for (int i = 0; i < 8; ++i) kv[i] = __builtin_nontemporal_load((const f32x4*)(kr + (i * 16 + l16) * 4));
;             }
;             float a0 = 0.f, a1 = 0.f, a2 = 0.f, a3 = 0.f;
; #pragma unroll
;             for (int i = 0; i < 8; ++i) {
;                 const int d = (i * 16 + l16) * 4;
;                 const f32x4 q0 = *(const f32x4*)(qs + d), q1 = *(const f32x4*)(qs + 512 + d), q2 = *(const f32x4*)(qs + 1024 + d), q3 = *(const f32x4*)(qs + 1536 + d);
;                 a0 += cv[i][0] * q0[0] + cv[i][1] * q0[1] + cv[i][2] * q0[2] + cv[i][3] * q0[3];
;                 a1 += cv[i][0] * q1[0] + cv[i][1] * q1[1] + cv[i][2] * q1[2] + cv[i][3] * q1[3];
;                 a2 += cv[i][0] * q2[0] + cv[i][1] * q2[1] + cv[i][2] * q2[2] + cv[i][3] * q2[3];
;                 a3 += cv[i][0] * q3[0] + cv[i][1] * q3[1] + cv[i][2] * q3[2] + cv[i][3] * q3[3];
;             }
.LBB0_1224:
	v_ashrrev_i32_e32 v79, 31, v78
	v_lshlrev_b64 v[2:3], 13, v[78:79]
	v_lshl_add_u64 v[84:85], v[76:77], 0, v[2:3]
	global_load_dwordx4 v[30:33], v[84:85], off nt
	global_load_dwordx4 v[26:29], v[84:85], off offset:256 nt
	global_load_dwordx4 v[22:25], v[84:85], off offset:512 nt
	global_load_dwordx4 v[18:21], v[84:85], off offset:768 nt
	global_load_dwordx4 v[14:17], v[84:85], off offset:1024 nt
	global_load_dwordx4 v[10:13], v[84:85], off offset:1280 nt
	global_load_dwordx4 v[6:9], v[84:85], off offset:1536 nt
	global_load_dwordx4 v[2:5], v[84:85], off offset:1792 nt
	ds_read_b128 v[84:87], v83
	ds_read_b128 v[96:99], v83 offset:2048
	ds_read_b128 v[100:103], v83 offset:4096
	ds_read_b128 v[104:107], v83 offset:6144
	ds_read_b128 v[108:111], v83 offset:256
	ds_read_b128 v[112:115], v83 offset:2304
	s_waitcnt lgkmcnt(4)
	v_pk_mov_b32 v[88:89], v[84:85], v[96:97] op_sel:[1,0]
	v_mov_b32_e32 v85, v97
	s_waitcnt vmcnt(15)
	v_pk_mul_f32 v[84:85], v[62:63], v[84:85]
	s_waitcnt lgkmcnt(2)
	v_pk_mov_b32 v[116:117], v[100:101], v[104:105] op_sel:[1,0]
	v_pk_fma_f32 v[84:85], v[62:63], v[88:89], v[84:85] op_sel:[1,0,0] op_sel_hi:[0,1,1]
	v_mov_b32_e32 v88, v86
	v_mov_b32_e32 v89, v98
	v_pk_fma_f32 v[84:85], v[64:65], v[88:89], v[84:85] op_sel_hi:[0,1,1]
	v_mov_b32_e32 v88, v65
	v_mov_b32_e32 v98, v87
	v_pk_fma_f32 v[84:85], v[88:89], v[98:99], v[84:85] op_sel_hi:[0,1,1]
	v_pk_add_f32 v[128:129], v[84:85], 0 op_sel_hi:[1,0]
	ds_read_b128 v[84:87], v83 offset:4352
	ds_read_b128 v[96:99], v83 offset:6400
	v_mov_b32_e32 v101, v105
	v_pk_mul_f32 v[100:101], v[62:63], v[100:101]
	s_waitcnt vmcnt(13)
	v_mov_b32_e32 v190, v57
	v_pk_fma_f32 v[62:63], v[62:63], v[116:117], v[100:101] op_sel:[1,0,0] op_sel_hi:[0,1,1]
	v_mov_b32_e32 v100, v102
	v_mov_b32_e32 v101, v106
	v_pk_fma_f32 v[62:63], v[64:65], v[100:101], v[62:63] op_sel_hi:[0,1,1]
	v_mov_b32_e32 v106, v103
	s_waitcnt lgkmcnt(2)
	v_pk_mov_b32 v[64:65], v[108:109], v[112:113] op_sel:[1,0]
	v_mov_b32_e32 v109, v113
	s_waitcnt lgkmcnt(0)
	v_pk_mov_b32 v[100:101], v[84:85], v[96:97] op_sel:[1,0]
	v_mov_b32_e32 v85, v97
	v_pk_fma_f32 v[62:63], v[88:89], v[106:107], v[62:63] op_sel_hi:[0,1,1]
	v_pk_mul_f32 v[88:89], v[58:59], v[108:109]
	v_pk_mul_f32 v[84:85], v[58:59], v[84:85]
	v_pk_fma_f32 v[64:65], v[58:59], v[64:65], v[88:89] op_sel:[1,0,0] op_sel_hi:[0,1,1]
	v_mov_b32_e32 v88, v110
	v_mov_b32_e32 v89, v114
	v_pk_fma_f32 v[58:59], v[58:59], v[100:101], v[84:85] op_sel:[1,0,0] op_sel_hi:[0,1,1]
	v_mov_b32_e32 v84, v86
	v_mov_b32_e32 v85, v98
	v_pk_fma_f32 v[64:65], v[60:61], v[88:89], v[64:65] op_sel_hi:[0,1,1]
	v_mov_b32_e32 v88, v61
	v_mov_b32_e32 v114, v111
	v_pk_fma_f32 v[58:59], v[60:61], v[84:85], v[58:59] op_sel_hi:[0,1,1]
	v_mov_b32_e32 v98, v87
	v_pk_fma_f32 v[64:65], v[88:89], v[114:115], v[64:65] op_sel_hi:[0,1,1]
	v_pk_fma_f32 v[88:89], v[88:89], v[98:99], v[58:59] op_sel_hi:[0,1,1]
	ds_read_b128 v[58:61], v83 offset:512
	ds_read_b128 v[84:87], v83 offset:2560
	ds_read_b128 v[96:99], v83 offset:4608
	ds_read_b128 v[100:103], v83 offset:6656
	ds_read_b128 v[104:107], v83 offset:768
	ds_read_b128 v[108:111], v83 offset:2816
	s_waitcnt lgkmcnt(4)
	v_pk_mov_b32 v[112:113], v[58:59], v[84:85] op_sel:[1,0]
	v_mov_b32_e32 v59, v85
	v_pk_mul_f32 v[58:59], v[54:55], v[58:59]
	v_mov_b32_e32 v84, v60
	v_pk_fma_f32 v[58:59], v[54:55], v[112:113], v[58:59] op_sel:[1,0,0] op_sel_hi:[0,1,1]
	v_mov_b32_e32 v85, v86
	v_pk_fma_f32 v[84:85], v[56:57], v[84:85], v[58:59] op_sel_hi:[0,1,1]
	v_mov_b32_e32 v86, v61
	ds_read_b128 v[58:61], v83 offset:4864
	ds_read_b128 v[112:115], v83 offset:6912
	s_waitcnt lgkmcnt(4)
	v_pk_mov_b32 v[116:117], v[96:97], v[100:101] op_sel:[1,0]
	v_mov_b32_e32 v97, v101
	v_pk_mul_f32 v[96:97], v[54:55], v[96:97]
	v_pk_add_f32 v[64:65], v[128:129], v[64:65]
	v_pk_fma_f32 v[54:55], v[54:55], v[116:117], v[96:97] op_sel:[1,0,0] op_sel_hi:[0,1,1]
	v_mov_b32_e32 v96, v98
	v_mov_b32_e32 v97, v102
	v_pk_fma_f32 v[100:101], v[56:57], v[96:97], v[54:55] op_sel_hi:[0,1,1]
	s_waitcnt lgkmcnt(2)
	v_pk_mov_b32 v[54:55], v[104:105], v[108:109] op_sel:[1,0]
	v_mov_b32_e32 v105, v109
	s_waitcnt vmcnt(12)
	v_pk_mul_f32 v[56:57], v[50:51], v[104:105]
	v_mov_b32_e32 v102, v99
	v_pk_fma_f32 v[104:105], v[50:51], v[54:55], v[56:57] op_sel:[1,0,0] op_sel_hi:[0,1,1]
	s_waitcnt lgkmcnt(0)
	v_pk_mov_b32 v[54:55], v[58:59], v[112:113] op_sel:[1,0]
	v_mov_b32_e32 v59, v113
	v_pk_mul_f32 v[56:57], v[50:51], v[58:59]
	v_mov_b32_e32 v108, v106
	v_pk_fma_f32 v[50:51], v[50:51], v[54:55], v[56:57] op_sel:[1,0,0] op_sel_hi:[0,1,1]
	ds_read_b128 v[54:57], v83 offset:1024
	ds_read_b128 v[96:99], v83 offset:3072
	ds_read_b128 v[116:119], v83 offset:5120
	ds_read_b128 v[120:123], v83 offset:7168
	ds_read_b128 v[124:127], v83 offset:1280
	v_mov_b32_e32 v109, v110
	v_pk_fma_f32 v[84:85], v[190:191], v[86:87], v[84:85] op_sel_hi:[0,1,1]
	v_mov_b32_e32 v58, v60
	s_waitcnt lgkmcnt(4)
	v_mov_b32_e32 v112, v54
	ds_read_b128 v[134:137], v83 offset:3328
	ds_read_b128 v[138:141], v83 offset:5376
	s_waitcnt lgkmcnt(5)
	v_mov_b32_e32 v113, v97
	v_pk_add_f32 v[64:65], v[64:65], v[84:85]
	v_pk_fma_f32 v[84:85], v[52:53], v[108:109], v[104:105] op_sel_hi:[0,1,1]
	v_mov_b32_e32 v60, v53
	v_mov_b32_e32 v110, v107
	s_waitcnt vmcnt(11)
	v_pk_mul_f32 v[112:113], v[46:47], v[112:113]
	v_pk_fma_f32 v[84:85], v[60:61], v[110:111], v[84:85] op_sel_hi:[0,1,1]
	v_pk_mov_b32 v[54:55], v[54:55], v[96:97] op_sel:[1,0]
	ds_read_b128 v[142:145], v83 offset:7424
	v_pk_add_f32 v[64:65], v[64:65], v[84:85]
	v_pk_fma_f32 v[54:55], v[46:47], v[54:55], v[112:113] op_sel:[1,0,0] op_sel_hi:[0,1,1]
	v_mov_b32_e32 v84, v56
	v_mov_b32_e32 v85, v98
	v_mov_b32_e32 v59, v114
	s_waitcnt lgkmcnt(5)
; DEV void attn_sample_item(const Params& p, int item, unsigned char* lds) {
;     ...
;             for (int i = 0; i < 8; ++i) {
;                 const int d = (i * 16 + l16) * 4;
;                 const f32x4 q0 = *(const f32x4*)(qs + d), q1 = *(const f32x4*)(qs + 512 + d), q2 = *(const f32x4*)(qs + 1024 + d), q3 = *(const f32x4*)(qs + 1536 + d);
;                 a0 += cv[i][0] * q0[0] + cv[i][1] * q0[1] + cv[i][2] * q0[2] + cv[i][3] * q0[3];
;                 a1 += cv[i][0] * q1[0] + cv[i][1] * q1[1] + cv[i][2] * q1[2] + cv[i][3] * q1[3];
;                 a2 += cv[i][0] * q2[0] + cv[i][1] * q2[1] + cv[i][2] * q2[2] + cv[i][3] * q2[3];
;                 a3 += cv[i][0] * q3[0] + cv[i][1] * q3[1] + cv[i][2] * q3[2] + cv[i][3] * q3[3];
;             }
; #pragma unroll
;             for (int o = 1; o < 16; o <<= 1) { a0 += __shfl_xor(a0, o); a1 += __shfl_xor(a1, o); a2 += __shfl_xor(a2, o); a3 += __shfl_xor(a3, o); }
;             if (l16 == 0) *(f32x4*)(pm + m * 4) = (f32x4){a0, a1, a2, a3};
	v_mov_b32_e32 v146, v116
	s_waitcnt lgkmcnt(4)
	v_mov_b32_e32 v147, v121
	v_pk_fma_f32 v[54:55], v[48:49], v[84:85], v[54:55] op_sel_hi:[0,1,1]
	v_mov_b32_e32 v56, v49
	v_mov_b32_e32 v98, v57
	v_pk_add_f32 v[62:63], v[62:63], 0 op_sel_hi:[1,0]
	v_pk_mul_f32 v[192:193], v[46:47], v[146:147]
	v_pk_fma_f32 v[54:55], v[56:57], v[98:99], v[54:55] op_sel_hi:[0,1,1]
	v_pk_fma_f32 v[50:51], v[52:53], v[58:59], v[50:51] op_sel_hi:[0,1,1]
	v_pk_mov_b32 v[52:53], v[116:117], v[120:121] op_sel:[1,0]
	v_pk_add_f32 v[54:55], v[64:65], v[54:55]
	s_waitcnt lgkmcnt(2)
	v_pk_mov_b32 v[64:65], v[124:125], v[134:135] op_sel:[1,0]
	v_mov_b32_e32 v125, v135
	v_pk_add_f32 v[62:63], v[62:63], v[88:89]
	v_pk_fma_f32 v[88:89], v[190:191], v[102:103], v[100:101] op_sel_hi:[0,1,1]
	v_mov_b32_e32 v114, v61
	v_pk_fma_f32 v[46:47], v[46:47], v[52:53], v[192:193] op_sel:[1,0,0] op_sel_hi:[0,1,1]
	v_mov_b32_e32 v52, v118
	v_mov_b32_e32 v53, v122
	s_waitcnt vmcnt(10)
	v_pk_mul_f32 v[84:85], v[42:43], v[124:125]
	v_pk_add_f32 v[62:63], v[62:63], v[88:89]
	v_pk_fma_f32 v[50:51], v[60:61], v[114:115], v[50:51] op_sel_hi:[0,1,1]
	v_pk_fma_f32 v[46:47], v[48:49], v[52:53], v[46:47] op_sel_hi:[0,1,1]
	v_mov_b32_e32 v122, v119
	ds_read_b128 v[146:149], v83 offset:1536
	ds_read_b128 v[150:153], v83 offset:1792
	ds_read_b128 v[154:157], v83 offset:3584
	ds_read_b128 v[170:173], v83 offset:3840
	ds_read_b128 v[174:177], v83 offset:5632
	ds_read_b128 v[178:181], v83 offset:5888
	ds_read_b128 v[182:185], v83 offset:7680
	ds_read_b128 v[186:189], v83 offset:7936
	v_pk_fma_f32 v[64:65], v[42:43], v[64:65], v[84:85] op_sel:[1,0,0] op_sel_hi:[0,1,1]
	v_mov_b32_e32 v84, v126
	v_mov_b32_e32 v85, v136
	v_pk_add_f32 v[50:51], v[62:63], v[50:51]
	v_pk_fma_f32 v[46:47], v[56:57], v[122:123], v[46:47] op_sel_hi:[0,1,1]
	s_waitcnt lgkmcnt(8)
	v_pk_mov_b32 v[48:49], v[138:139], v[142:143] op_sel:[1,0]
	v_mov_b32_e32 v139, v143
	v_pk_fma_f32 v[64:65], v[44:45], v[84:85], v[64:65] op_sel_hi:[0,1,1]
	v_mov_b32_e32 v84, v45
	v_mov_b32_e32 v136, v127
	v_pk_add_f32 v[46:47], v[50:51], v[46:47]
	v_pk_mul_f32 v[50:51], v[42:43], v[138:139]
	v_pk_fma_f32 v[64:65], v[84:85], v[136:137], v[64:65] op_sel_hi:[0,1,1]
	v_pk_fma_f32 v[42:43], v[42:43], v[48:49], v[50:51] op_sel:[1,0,0] op_sel_hi:[0,1,1]
	v_mov_b32_e32 v48, v140
	v_mov_b32_e32 v49, v144
	v_pk_add_f32 v[54:55], v[54:55], v[64:65]
	s_waitcnt lgkmcnt(5)
	v_pk_mov_b32 v[64:65], v[146:147], v[154:155] op_sel:[1,0]
	v_mov_b32_e32 v147, v155
	v_pk_fma_f32 v[42:43], v[44:45], v[48:49], v[42:43] op_sel_hi:[0,1,1]
	v_mov_b32_e32 v144, v141
	s_waitcnt vmcnt(9)
	v_pk_mul_f32 v[86:87], v[38:39], v[146:147]
	v_pk_fma_f32 v[42:43], v[84:85], v[144:145], v[42:43] op_sel_hi:[0,1,1]
	s_waitcnt lgkmcnt(1)
	v_pk_mov_b32 v[44:45], v[174:175], v[182:183] op_sel:[1,0]
	v_mov_b32_e32 v175, v183
	v_pk_fma_f32 v[64:65], v[38:39], v[64:65], v[86:87] op_sel:[1,0,0] op_sel_hi:[0,1,1]
	v_mov_b32_e32 v86, v148
	v_mov_b32_e32 v87, v156
	v_pk_add_f32 v[42:43], v[46:47], v[42:43]
	v_pk_mul_f32 v[46:47], v[38:39], v[174:175]
	v_pk_fma_f32 v[64:65], v[40:41], v[86:87], v[64:65] op_sel_hi:[0,1,1]
	v_mov_b32_e32 v86, v41
	v_mov_b32_e32 v156, v149
	v_pk_fma_f32 v[38:39], v[38:39], v[44:45], v[46:47] op_sel:[1,0,0] op_sel_hi:[0,1,1]
	v_mov_b32_e32 v44, v176
	v_mov_b32_e32 v45, v184
	v_pk_fma_f32 v[64:65], v[86:87], v[156:157], v[64:65] op_sel_hi:[0,1,1]
	v_pk_fma_f32 v[38:39], v[40:41], v[44:45], v[38:39] op_sel_hi:[0,1,1]
	v_mov_b32_e32 v184, v177
	v_pk_add_f32 v[54:55], v[54:55], v[64:65]
	v_pk_mov_b32 v[64:65], v[150:151], v[170:171] op_sel:[1,0]
	v_mov_b32_e32 v151, v171
	v_pk_fma_f32 v[38:39], v[86:87], v[184:185], v[38:39] op_sel_hi:[0,1,1]
	s_waitcnt lgkmcnt(0)
	v_pk_mov_b32 v[40:41], v[178:179], v[186:187] op_sel:[1,0]
	v_mov_b32_e32 v179, v187
	s_waitcnt vmcnt(8)
	v_pk_mul_f32 v[96:97], v[34:35], v[150:151]
	v_pk_add_f32 v[38:39], v[42:43], v[38:39]
	v_pk_mul_f32 v[42:43], v[34:35], v[178:179]
	v_pk_fma_f32 v[64:65], v[34:35], v[64:65], v[96:97] op_sel:[1,0,0] op_sel_hi:[0,1,1]
	v_mov_b32_e32 v96, v152
	v_mov_b32_e32 v97, v172
	v_pk_fma_f32 v[34:35], v[34:35], v[40:41], v[42:43] op_sel:[1,0,0] op_sel_hi:[0,1,1]
	v_mov_b32_e32 v40, v180
	v_mov_b32_e32 v41, v188
	v_pk_fma_f32 v[64:65], v[36:37], v[96:97], v[64:65] op_sel_hi:[0,1,1]
	v_mov_b32_e32 v96, v37
	v_mov_b32_e32 v172, v153
	v_pk_fma_f32 v[34:35], v[36:37], v[40:41], v[34:35] op_sel_hi:[0,1,1]
	v_mov_b32_e32 v188, v181
	v_pk_fma_f32 v[64:65], v[96:97], v[172:173], v[64:65] op_sel_hi:[0,1,1]
	v_pk_fma_f32 v[34:35], v[96:97], v[188:189], v[34:35] op_sel_hi:[0,1,1]
	v_pk_add_f32 v[54:55], v[54:55], v[64:65]
	v_pk_add_f32 v[34:35], v[38:39], v[34:35]
	s_nop 0
	v_mov_b32_dpp v64, v54 quad_perm:[1,0,3,2] row_mask:0xf bank_mask:0xf
	v_mov_b32_dpp v65, v55 quad_perm:[1,0,3,2] row_mask:0xf bank_mask:0xf
	v_mov_b32_dpp v36, v34 quad_perm:[1,0,3,2] row_mask:0xf bank_mask:0xf
	v_mov_b32_dpp v37, v35 quad_perm:[1,0,3,2] row_mask:0xf bank_mask:0xf
	s_waitcnt lgkmcnt(2)
	v_pk_add_f32 v[38:39], v[54:55], v[64:65]
	s_nop 1
	v_mov_b32_dpp v40, v38 quad_perm:[2,3,0,1] row_mask:0xf bank_mask:0xf
	s_waitcnt lgkmcnt(1)
	v_pk_add_f32 v[34:35], v[34:35], v[36:37]
	v_mov_b32_dpp v41, v39 quad_perm:[2,3,0,1] row_mask:0xf bank_mask:0xf
	s_nop 0
	v_mov_b32_dpp v36, v34 quad_perm:[2,3,0,1] row_mask:0xf bank_mask:0xf
	v_mov_b32_dpp v37, v35 quad_perm:[2,3,0,1] row_mask:0xf bank_mask:0xf
	s_waitcnt lgkmcnt(2)
	v_pk_add_f32 v[38:39], v[38:39], v[40:41]
	s_nop 1
	v_mov_b32_dpp v194, v38 row_shr:4 row_mask:0xf bank_mask:0xa
	s_nop 0
	v_mov_b32_dpp v194, v38 row_shl:4 row_mask:0xf bank_mask:0x5
	v_mov_b32_e32 v40, v194
	s_waitcnt lgkmcnt(1)
	v_pk_add_f32 v[36:37], v[34:35], v[36:37]
	v_mov_b32_dpp v194, v39 row_shr:4 row_mask:0xf bank_mask:0xa
	v_mov_b32_dpp v194, v39 row_shl:4 row_mask:0xf bank_mask:0x5
	v_mov_b32_e32 v41, v194
	v_mov_b32_dpp v194, v36 row_shr:4 row_mask:0xf bank_mask:0xa
	v_mov_b32_dpp v194, v36 row_shl:4 row_mask:0xf bank_mask:0x5
	v_mov_b32_e32 v42, v194
	v_mov_b32_dpp v194, v37 row_shr:4 row_mask:0xf bank_mask:0xa
	v_mov_b32_dpp v194, v37 row_shl:4 row_mask:0xf bank_mask:0x5
	v_mov_b32_e32 v43, v194
	s_waitcnt lgkmcnt(2)
	v_pk_add_f32 v[34:35], v[38:39], v[40:41]
	s_waitcnt lgkmcnt(0)
	v_pk_add_f32 v[38:39], v[36:37], v[42:43]
	v_mov_b32_dpp v36, v34 row_ror:8 row_mask:0xf bank_mask:0xf
	v_mov_b32_dpp v37, v35 row_ror:8 row_mask:0xf bank_mask:0xf
	v_mov_b32_dpp v40, v38 row_ror:8 row_mask:0xf bank_mask:0xf
	v_mov_b32_dpp v41, v39 row_ror:8 row_mask:0xf bank_mask:0xf
	s_and_saveexec_b64 s[4:5], vcc
	s_cbranch_execz .LBB0_1223
	v_add_u32_e32 v42, s12, v66
	s_waitcnt lgkmcnt(0)
	v_pk_add_f32 v[38:39], v[38:39], v[40:41]
	v_pk_add_f32 v[36:37], v[34:35], v[36:37]
	ds_write_b128 v42, v[36:39]
	s_branch .LBB0_1223
; DEV void attn_sample_item(const Params& p, int item, unsigned char* lds) {
;     ...
;             float a0 = 0.f, a1 = 0.f, a2 = 0.f, a3 = 0.f;
; #pragma unroll
;             for (int i = 0; i < 8; ++i) {
;                 const int d = (i * 16 + l16) * 4;
;                 const f32x4 q0 = *(const f32x4*)(qs + d), q1 = *(const f32x4*)(qs + 512 + d), q2 = *(const f32x4*)(qs + 1024 + d), q3 = *(const f32x4*)(qs + 1536 + d);
;                 a0 += cv[i][0] * q0[0] + cv[i][1] * q0[1] + cv[i][2] * q0[2] + cv[i][3] * q0[3];
;                 a1 += cv[i][0] * q1[0] + cv[i][1] * q1[1] + cv[i][2] * q1[2] + cv[i][3] * q1[3];
;                 a2 += cv[i][0] * q2[0] + cv[i][1] * q2[1] + cv[i][2] * q2[2] + cv[i][3] * q2[3];
;                 a3 += cv[i][0] * q3[0] + cv[i][1] * q3[1] + cv[i][2] * q3[2] + cv[i][3] * q3[3];
;             }
.LBB0_1226:
	ds_read_b128 v[34:37], v83
	ds_read_b128 v[38:41], v83 offset:2048
	ds_read_b128 v[42:45], v83 offset:4096
	ds_read_b128 v[46:49], v83 offset:6144
	ds_read_b128 v[50:53], v83 offset:256
	ds_read_b128 v[54:57], v83 offset:2304
	s_waitcnt lgkmcnt(4)
	v_pk_mov_b32 v[58:59], v[34:35], v[38:39] op_sel:[1,0]
	v_mov_b32_e32 v35, v39
	v_pk_mul_f32 v[34:35], v[30:31], v[34:35]
	v_mov_b32_e32 v38, v36
	v_pk_fma_f32 v[34:35], v[30:31], v[58:59], v[34:35] op_sel:[1,0,0] op_sel_hi:[0,1,1]
	v_mov_b32_e32 v39, v40
	v_pk_fma_f32 v[34:35], v[32:33], v[38:39], v[34:35] op_sel_hi:[0,1,1]
	v_mov_b32_e32 v58, v33
	v_mov_b32_e32 v40, v37
	s_waitcnt lgkmcnt(2)
	v_pk_mov_b32 v[60:61], v[42:43], v[46:47] op_sel:[1,0]
	v_mov_b32_e32 v43, v47
	v_pk_fma_f32 v[34:35], v[58:59], v[40:41], v[34:35] op_sel_hi:[0,1,1]
	v_pk_mul_f32 v[42:43], v[30:31], v[42:43]
	v_pk_add_f32 v[64:65], v[34:35], 0 op_sel_hi:[1,0]
	ds_read_b128 v[34:37], v83 offset:4352
	ds_read_b128 v[38:41], v83 offset:6400
	v_pk_fma_f32 v[30:31], v[30:31], v[60:61], v[42:43] op_sel:[1,0,0] op_sel_hi:[0,1,1]
	v_mov_b32_e32 v42, v44
	v_mov_b32_e32 v43, v48
	v_pk_fma_f32 v[30:31], v[32:33], v[42:43], v[30:31] op_sel_hi:[0,1,1]
	s_waitcnt lgkmcnt(2)
	v_pk_mov_b32 v[32:33], v[50:51], v[54:55] op_sel:[1,0]
	v_mov_b32_e32 v51, v55
	v_pk_mul_f32 v[42:43], v[26:27], v[50:51]
	v_mov_b32_e32 v48, v45
	v_pk_fma_f32 v[32:33], v[26:27], v[32:33], v[42:43] op_sel:[1,0,0] op_sel_hi:[0,1,1]
	v_mov_b32_e32 v42, v52
	v_mov_b32_e32 v43, v56
	v_pk_fma_f32 v[32:33], v[28:29], v[42:43], v[32:33] op_sel_hi:[0,1,1]
	v_mov_b32_e32 v42, v29
	v_mov_b32_e32 v56, v53
	v_pk_fma_f32 v[88:89], v[42:43], v[56:57], v[32:33] op_sel_hi:[0,1,1]
	s_waitcnt lgkmcnt(0)
	v_pk_mov_b32 v[32:33], v[34:35], v[38:39] op_sel:[1,0]
	v_mov_b32_e32 v35, v39
	v_pk_mul_f32 v[34:35], v[26:27], v[34:35]
	v_pk_fma_f32 v[30:31], v[58:59], v[48:49], v[30:31] op_sel_hi:[0,1,1]
	v_pk_fma_f32 v[26:27], v[26:27], v[32:33], v[34:35] op_sel:[1,0,0] op_sel_hi:[0,1,1]
	v_mov_b32_e32 v32, v36
	v_mov_b32_e32 v33, v40
	v_pk_fma_f32 v[26:27], v[28:29], v[32:33], v[26:27] op_sel_hi:[0,1,1]
	v_mov_b32_e32 v40, v37
	v_pk_fma_f32 v[128:129], v[42:43], v[40:41], v[26:27] op_sel_hi:[0,1,1]
	ds_read_b128 v[26:29], v83 offset:512
	ds_read_b128 v[32:35], v83 offset:2560
	ds_read_b128 v[36:39], v83 offset:4608
	ds_read_b128 v[40:43], v83 offset:6656
	ds_read_b128 v[44:47], v83 offset:768
	ds_read_b128 v[48:51], v83 offset:2816
	s_waitcnt lgkmcnt(4)
	v_pk_mov_b32 v[52:53], v[26:27], v[32:33] op_sel:[1,0]
	v_mov_b32_e32 v27, v33
	v_pk_mul_f32 v[26:27], v[22:23], v[26:27]
	v_mov_b32_e32 v32, v28
	v_pk_fma_f32 v[26:27], v[22:23], v[52:53], v[26:27] op_sel:[1,0,0] op_sel_hi:[0,1,1]
	v_mov_b32_e32 v33, v34
	v_pk_fma_f32 v[32:33], v[24:25], v[32:33], v[26:27] op_sel_hi:[0,1,1]
	v_mov_b32_e32 v34, v29
	ds_read_b128 v[26:29], v83 offset:4864
	ds_read_b128 v[52:55], v83 offset:6912
	s_waitcnt lgkmcnt(4)
	v_pk_mov_b32 v[56:57], v[36:37], v[40:41] op_sel:[1,0]
	v_mov_b32_e32 v37, v41
	v_pk_mul_f32 v[36:37], v[22:23], v[36:37]
	v_mov_b32_e32 v66, v25
	v_pk_fma_f32 v[22:23], v[22:23], v[56:57], v[36:37] op_sel:[1,0,0] op_sel_hi:[0,1,1]
	v_mov_b32_e32 v36, v38
	v_mov_b32_e32 v37, v42
	v_pk_fma_f32 v[40:41], v[24:25], v[36:37], v[22:23] op_sel_hi:[0,1,1]
	s_waitcnt lgkmcnt(2)
	v_pk_mov_b32 v[22:23], v[44:45], v[48:49] op_sel:[1,0]
	v_mov_b32_e32 v45, v49
	v_pk_mul_f32 v[24:25], v[18:19], v[44:45]
	v_mov_b32_e32 v42, v39
	v_pk_fma_f32 v[44:45], v[18:19], v[22:23], v[24:25] op_sel:[1,0,0] op_sel_hi:[0,1,1]
	s_waitcnt lgkmcnt(0)
	v_pk_mov_b32 v[22:23], v[26:27], v[52:53] op_sel:[1,0]
	v_mov_b32_e32 v27, v53
	v_pk_mul_f32 v[24:25], v[18:19], v[26:27]
	v_mov_b32_e32 v48, v46
	v_pk_fma_f32 v[18:19], v[18:19], v[22:23], v[24:25] op_sel:[1,0,0] op_sel_hi:[0,1,1]
	ds_read_b128 v[22:25], v83 offset:1024
	ds_read_b128 v[36:39], v83 offset:3072
	ds_read_b128 v[56:59], v83 offset:5120
	ds_read_b128 v[60:63], v83 offset:7168
	ds_read_b128 v[76:79], v83 offset:1280
	v_mov_b32_e32 v49, v50
	v_mov_b32_e32 v26, v28
	s_waitcnt lgkmcnt(4)
	v_mov_b32_e32 v52, v22
	ds_read_b128 v[84:87], v83 offset:3328
	ds_read_b128 v[96:99], v83 offset:5376
	s_waitcnt lgkmcnt(5)
	v_mov_b32_e32 v53, v37
	v_pk_add_f32 v[64:65], v[64:65], v[88:89]
	v_pk_fma_f32 v[32:33], v[66:67], v[34:35], v[32:33] op_sel_hi:[0,1,1]
	v_pk_fma_f32 v[34:35], v[20:21], v[48:49], v[44:45] op_sel_hi:[0,1,1]
	v_mov_b32_e32 v28, v21
	v_mov_b32_e32 v50, v47
	v_pk_mul_f32 v[52:53], v[14:15], v[52:53]
	v_pk_add_f32 v[32:33], v[64:65], v[32:33]
	v_pk_fma_f32 v[34:35], v[28:29], v[50:51], v[34:35] op_sel_hi:[0,1,1]
	v_pk_mov_b32 v[22:23], v[22:23], v[36:37] op_sel:[1,0]
	ds_read_b128 v[100:103], v83 offset:7424
	v_pk_add_f32 v[32:33], v[32:33], v[34:35]
	v_pk_fma_f32 v[22:23], v[14:15], v[22:23], v[52:53] op_sel:[1,0,0] op_sel_hi:[0,1,1]
	v_mov_b32_e32 v34, v24
	v_mov_b32_e32 v35, v38
	v_mov_b32_e32 v27, v54
	s_waitcnt lgkmcnt(5)
	v_mov_b32_e32 v104, v56
	s_waitcnt lgkmcnt(4)
	v_mov_b32_e32 v105, v61
	v_pk_fma_f32 v[22:23], v[16:17], v[34:35], v[22:23] op_sel_hi:[0,1,1]
	v_mov_b32_e32 v24, v17
	v_mov_b32_e32 v38, v25
	v_pk_add_f32 v[30:31], v[30:31], 0 op_sel_hi:[1,0]
	v_pk_mul_f32 v[142:143], v[14:15], v[104:105]
	v_pk_fma_f32 v[22:23], v[24:25], v[38:39], v[22:23] op_sel_hi:[0,1,1]
	v_pk_fma_f32 v[18:19], v[20:21], v[26:27], v[18:19] op_sel_hi:[0,1,1]
	v_pk_mov_b32 v[20:21], v[56:57], v[60:61] op_sel:[1,0]
	v_pk_add_f32 v[22:23], v[32:33], v[22:23]
	s_waitcnt lgkmcnt(2)
; DEV void attn_sample_item(const Params& p, int item, unsigned char* lds) {
;     ...
;             for (int i = 0; i < 8; ++i) {
;                 const int d = (i * 16 + l16) * 4;
;                 const f32x4 q0 = *(const f32x4*)(qs + d), q1 = *(const f32x4*)(qs + 512 + d), q2 = *(const f32x4*)(qs + 1024 + d), q3 = *(const f32x4*)(qs + 1536 + d);
;                 a0 += cv[i][0] * q0[0] + cv[i][1] * q0[1] + cv[i][2] * q0[2] + cv[i][3] * q0[3];
;                 a1 += cv[i][0] * q1[0] + cv[i][1] * q1[1] + cv[i][2] * q1[2] + cv[i][3] * q1[3];
;                 a2 += cv[i][0] * q2[0] + cv[i][1] * q2[1] + cv[i][2] * q2[2] + cv[i][3] * q2[3];
;                 a3 += cv[i][0] * q3[0] + cv[i][1] * q3[1] + cv[i][2] * q3[2] + cv[i][3] * q3[3];
;             }
; #pragma unroll
;             for (int o = 1; o < 16; o <<= 1) { a0 += __shfl_xor(a0, o); a1 += __shfl_xor(a1, o); a2 += __shfl_xor(a2, o); a3 += __shfl_xor(a3, o); }
;             if (l16 == 0) *(f32x4*)(pm + m * 4) = (f32x4){a0, a1, a2, a3};
	v_pk_mov_b32 v[32:33], v[76:77], v[84:85] op_sel:[1,0]
	v_mov_b32_e32 v77, v85
	v_pk_add_f32 v[30:31], v[30:31], v[128:129]
	v_pk_fma_f32 v[40:41], v[66:67], v[42:43], v[40:41] op_sel_hi:[0,1,1]
	v_mov_b32_e32 v54, v29
	v_pk_fma_f32 v[14:15], v[14:15], v[20:21], v[142:143] op_sel:[1,0,0] op_sel_hi:[0,1,1]
	v_mov_b32_e32 v20, v58
	v_mov_b32_e32 v21, v62
	v_pk_mul_f32 v[34:35], v[10:11], v[76:77]
	v_pk_add_f32 v[30:31], v[30:31], v[40:41]
	v_pk_fma_f32 v[18:19], v[28:29], v[54:55], v[18:19] op_sel_hi:[0,1,1]
	v_pk_fma_f32 v[14:15], v[16:17], v[20:21], v[14:15] op_sel_hi:[0,1,1]
	v_mov_b32_e32 v62, v59
	ds_read_b128 v[104:107], v83 offset:1536
	ds_read_b128 v[108:111], v83 offset:1792
	ds_read_b128 v[112:115], v83 offset:3584
	ds_read_b128 v[116:119], v83 offset:3840
	ds_read_b128 v[120:123], v83 offset:5632
	ds_read_b128 v[124:127], v83 offset:5888
	ds_read_b128 v[134:137], v83 offset:7680
	ds_read_b128 v[138:141], v83 offset:7936
	v_pk_fma_f32 v[32:33], v[10:11], v[32:33], v[34:35] op_sel:[1,0,0] op_sel_hi:[0,1,1]
	v_mov_b32_e32 v34, v78
	v_mov_b32_e32 v35, v86
	v_pk_add_f32 v[18:19], v[30:31], v[18:19]
	v_pk_fma_f32 v[14:15], v[24:25], v[62:63], v[14:15] op_sel_hi:[0,1,1]
	s_waitcnt lgkmcnt(8)
	v_pk_mov_b32 v[16:17], v[96:97], v[100:101] op_sel:[1,0]
	v_mov_b32_e32 v97, v101
	v_pk_fma_f32 v[32:33], v[12:13], v[34:35], v[32:33] op_sel_hi:[0,1,1]
	v_mov_b32_e32 v34, v13
	v_mov_b32_e32 v86, v79
	v_pk_add_f32 v[14:15], v[18:19], v[14:15]
	v_pk_mul_f32 v[18:19], v[10:11], v[96:97]
	v_pk_fma_f32 v[32:33], v[34:35], v[86:87], v[32:33] op_sel_hi:[0,1,1]
	v_pk_fma_f32 v[10:11], v[10:11], v[16:17], v[18:19] op_sel:[1,0,0] op_sel_hi:[0,1,1]
	v_mov_b32_e32 v16, v98
	v_mov_b32_e32 v17, v102
	v_pk_add_f32 v[22:23], v[22:23], v[32:33]
	s_waitcnt lgkmcnt(5)
	v_pk_mov_b32 v[32:33], v[104:105], v[112:113] op_sel:[1,0]
	v_mov_b32_e32 v105, v113
	v_pk_fma_f32 v[10:11], v[12:13], v[16:17], v[10:11] op_sel_hi:[0,1,1]
	v_mov_b32_e32 v102, v99
	v_pk_mul_f32 v[36:37], v[6:7], v[104:105]
	v_pk_fma_f32 v[10:11], v[34:35], v[102:103], v[10:11] op_sel_hi:[0,1,1]
	s_waitcnt lgkmcnt(1)
	v_pk_mov_b32 v[12:13], v[120:121], v[134:135] op_sel:[1,0]
	v_mov_b32_e32 v121, v135
	v_pk_fma_f32 v[32:33], v[6:7], v[32:33], v[36:37] op_sel:[1,0,0] op_sel_hi:[0,1,1]
	v_mov_b32_e32 v36, v106
	v_mov_b32_e32 v37, v114
	v_pk_add_f32 v[10:11], v[14:15], v[10:11]
	v_pk_mul_f32 v[14:15], v[6:7], v[120:121]
	v_pk_fma_f32 v[32:33], v[8:9], v[36:37], v[32:33] op_sel_hi:[0,1,1]
	v_mov_b32_e32 v36, v9
	v_mov_b32_e32 v114, v107
	v_pk_fma_f32 v[6:7], v[6:7], v[12:13], v[14:15] op_sel:[1,0,0] op_sel_hi:[0,1,1]
	v_mov_b32_e32 v12, v122
	v_mov_b32_e32 v13, v136
	v_pk_fma_f32 v[32:33], v[36:37], v[114:115], v[32:33] op_sel_hi:[0,1,1]
	v_pk_fma_f32 v[6:7], v[8:9], v[12:13], v[6:7] op_sel_hi:[0,1,1]
	v_mov_b32_e32 v136, v123
	v_pk_add_f32 v[22:23], v[22:23], v[32:33]
	v_pk_mov_b32 v[32:33], v[108:109], v[116:117] op_sel:[1,0]
	v_mov_b32_e32 v109, v117
	v_pk_fma_f32 v[6:7], v[36:37], v[136:137], v[6:7] op_sel_hi:[0,1,1]
	s_waitcnt lgkmcnt(0)
	v_pk_mov_b32 v[8:9], v[124:125], v[138:139] op_sel:[1,0]
	v_mov_b32_e32 v125, v139
	v_pk_mul_f32 v[38:39], v[2:3], v[108:109]
	v_pk_add_f32 v[6:7], v[10:11], v[6:7]
	v_pk_mul_f32 v[10:11], v[2:3], v[124:125]
	v_pk_fma_f32 v[32:33], v[2:3], v[32:33], v[38:39] op_sel:[1,0,0] op_sel_hi:[0,1,1]
	v_mov_b32_e32 v38, v110
	v_mov_b32_e32 v39, v118
	v_pk_fma_f32 v[2:3], v[2:3], v[8:9], v[10:11] op_sel:[1,0,0] op_sel_hi:[0,1,1]
	v_mov_b32_e32 v8, v126
	v_mov_b32_e32 v9, v140
	v_pk_fma_f32 v[32:33], v[4:5], v[38:39], v[32:33] op_sel_hi:[0,1,1]
	v_mov_b32_e32 v38, v5
	v_mov_b32_e32 v118, v111
	v_pk_fma_f32 v[2:3], v[4:5], v[8:9], v[2:3] op_sel_hi:[0,1,1]
	v_mov_b32_e32 v140, v127
	v_pk_fma_f32 v[32:33], v[38:39], v[118:119], v[32:33] op_sel_hi:[0,1,1]
	v_pk_fma_f32 v[2:3], v[38:39], v[140:141], v[2:3] op_sel_hi:[0,1,1]
	v_pk_add_f32 v[22:23], v[22:23], v[32:33]
	v_pk_add_f32 v[2:3], v[6:7], v[2:3]
	s_nop 0
	v_mov_b32_dpp v32, v22 quad_perm:[1,0,3,2] row_mask:0xf bank_mask:0xf
	v_mov_b32_dpp v33, v23 quad_perm:[1,0,3,2] row_mask:0xf bank_mask:0xf
	v_mov_b32_dpp v4, v2 quad_perm:[1,0,3,2] row_mask:0xf bank_mask:0xf
	v_mov_b32_dpp v5, v3 quad_perm:[1,0,3,2] row_mask:0xf bank_mask:0xf
	s_waitcnt lgkmcnt(2)
	v_pk_add_f32 v[6:7], v[22:23], v[32:33]
	s_nop 1
	v_mov_b32_dpp v8, v6 quad_perm:[2,3,0,1] row_mask:0xf bank_mask:0xf
	s_waitcnt lgkmcnt(1)
	v_pk_add_f32 v[2:3], v[2:3], v[4:5]
	v_mov_b32_dpp v9, v7 quad_perm:[2,3,0,1] row_mask:0xf bank_mask:0xf
	s_nop 0
	v_mov_b32_dpp v4, v2 quad_perm:[2,3,0,1] row_mask:0xf bank_mask:0xf
	v_mov_b32_dpp v5, v3 quad_perm:[2,3,0,1] row_mask:0xf bank_mask:0xf
	s_waitcnt lgkmcnt(2)
	v_pk_add_f32 v[6:7], v[6:7], v[8:9]
	s_nop 1
	v_mov_b32_dpp v194, v6 row_shr:4 row_mask:0xf bank_mask:0xa
	s_nop 0
	v_mov_b32_dpp v194, v6 row_shl:4 row_mask:0xf bank_mask:0x5
	v_mov_b32_e32 v8, v194
	s_waitcnt lgkmcnt(1)
	v_pk_add_f32 v[4:5], v[2:3], v[4:5]
	v_mov_b32_dpp v194, v7 row_shr:4 row_mask:0xf bank_mask:0xa
	v_mov_b32_dpp v194, v7 row_shl:4 row_mask:0xf bank_mask:0x5
	v_mov_b32_e32 v9, v194
	v_mov_b32_dpp v194, v4 row_shr:4 row_mask:0xf bank_mask:0xa
	v_mov_b32_dpp v194, v4 row_shl:4 row_mask:0xf bank_mask:0x5
	v_mov_b32_e32 v10, v194
	v_mov_b32_dpp v194, v5 row_shr:4 row_mask:0xf bank_mask:0xa
	v_mov_b32_dpp v194, v5 row_shl:4 row_mask:0xf bank_mask:0x5
	v_mov_b32_e32 v11, v194
	s_waitcnt lgkmcnt(2)
	v_pk_add_f32 v[2:3], v[6:7], v[8:9]
	s_waitcnt lgkmcnt(0)
	v_pk_add_f32 v[6:7], v[4:5], v[10:11]
	v_mov_b32_dpp v4, v2 row_ror:8 row_mask:0xf bank_mask:0xf
	v_mov_b32_dpp v5, v3 row_ror:8 row_mask:0xf bank_mask:0xf
	v_mov_b32_dpp v8, v6 row_ror:8 row_mask:0xf bank_mask:0xf
	v_mov_b32_dpp v9, v7 row_ror:8 row_mask:0xf bank_mask:0xf
	s_and_saveexec_b64 s[4:5], vcc
	s_cbranch_execz .LBB0_1228
	v_lshl_add_u32 v10, v74, 4, s30
	s_waitcnt lgkmcnt(0)
	v_pk_add_f32 v[6:7], v[6:7], v[8:9]
	v_pk_add_f32 v[4:5], v[2:3], v[4:5]
	ds_write_b128 v10, v[4:7] offset:9152
; DEV void attn_sample_item(const Params& p, int item, unsigned char* lds) {
;     ...
;     __syncthreads();
;     {
;         const int t = wid;
;         float v[4]; float mx = -3.0e38f;
; #pragma unroll
;         for (int i = 0; i < 4; ++i) { v[i] = pm[(i * 64 + lane) * 4 + t]; mx = fmaxf(mx, v[i]); }
;         mx = wave_max(mx);
;         float sm = 0.f;
; #pragma unroll
;         for (int i = 0; i < 4; ++i) { v[i] = __expf(v[i] - mx); sm += v[i]; }
;         sm = wave_sum(sm);
;         const float inv = 1.f / sm;
; #pragma unroll
;         for (int i = 0; i < 4; ++i) pm[(i * 64 + lane) * 4 + t] = v[i] * inv;
;     }
;     __syncthreads();
;     {
;         f32x4 acc[4][2];
; #pragma unroll
;         for (int t = 0; t < 4; ++t) { acc[t][0] = (f32x4){0.f, 0.f, 0.f, 0.f}; acc[t][1] = (f32x4){0.f, 0.f, 0.f, 0.f}; }
;         f32x4 va[4], vb[4];
; #pragma unroll
;         for (int i = 0; i < 4; ++i) { const float* vr = Vc + (size_t)(wid * 64 + i) * D; va[i] = __builtin_nontemporal_load((const f32x4*)(vr + lane * 4)); vb[i] = __builtin_nontemporal_load((const f32x4*)(vr + 256 + lane * 4)); }
.LBB0_1228:
	s_or_b64 exec, exec, s[4:5]
	v_ashrrev_i32_e32 v96, 6, v68
	v_lshlrev_b32_e32 v66, 4, v75
	v_lshlrev_b32_e32 v2, 2, v96
	v_add3_u32 v10, s30, v66, v2
	s_waitcnt lgkmcnt(0)
	s_barrier
	ds_read2st64_b32 v[2:3], v10 offset0:32 offset1:36
	ds_read2st64_b32 v[4:5], v10 offset0:40 offset1:44
	v_xor_b32_e32 v7, 32, v90
	v_cmp_lt_i32_e32 vcc, v7, v91
	s_lshl_b64 s[4:5], s[20:21], 2
	s_waitcnt lgkmcnt(1)
	v_max3_f32 v6, v2, s42, v3
	v_cndmask_b32_e32 v7, v90, v7, vcc
	s_waitcnt lgkmcnt(0)
	v_max3_f32 v6, v6, v4, v5
	v_lshlrev_b32_e32 v7, 2, v7
	ds_bpermute_b32 v8, v7, v6
	s_add_u32 s4, s10, s4
	v_lshlrev_b64 v[34:35], 2, v[70:71]
	s_addc_u32 s5, s11, s5
	v_mov_b32_e32 v52, 0
	s_waitcnt lgkmcnt(0)
	v_max_f32_e32 v8, v8, v8
	v_max_f32_e32 v6, v6, v8
	v_xor_b32_e32 v8, 16, v90
	v_cmp_lt_i32_e32 vcc, v8, v91
	v_lshlrev_b32_e32 v97, 4, v72
	v_add_u32_e32 v98, s37, v97
	v_cndmask_b32_e32 v8, v90, v8, vcc
	v_lshlrev_b32_e32 v8, 2, v8
	ds_bpermute_b32 v9, v8, v6
	v_mov_b32_e32 v53, v52
	v_mov_b32_e32 v88, v52
	v_mov_b32_e32 v89, v52
	v_mov_b32_e32 v76, v52
	s_waitcnt lgkmcnt(0)
	v_max_f32_e32 v9, v9, v9
	v_max_f32_e32 v6, v6, v9
	s_nop 1
	v_mov_b32_dpp v9, v6 row_ror:8 row_mask:0xf bank_mask:0xf
	v_mov_b32_e32 v77, v52
	v_mov_b32_e32 v86, v52
	v_mov_b32_e32 v87, v52
	v_mov_b32_e32 v74, v52
	s_waitcnt lgkmcnt(0)
	v_max_f32_e32 v9, v9, v9
	v_max_f32_e32 v6, v6, v9
	s_nop 1
	v_mov_b32_dpp v194, v6 row_shr:4 row_mask:0xf bank_mask:0xa
	s_nop 0
	v_mov_b32_dpp v194, v6 row_shl:4 row_mask:0xf bank_mask:0x5
	v_mov_b32_e32 v9, v194
	v_mov_b32_e32 v84, v52
	v_mov_b32_e32 v85, v52
	v_mov_b32_e32 v83, v52
	v_mov_b32_e32 v64, v52
	s_waitcnt lgkmcnt(0)
	v_max_f32_e32 v9, v9, v9
	v_max_f32_e32 v6, v6, v9
	s_nop 1
	v_mov_b32_dpp v9, v6 quad_perm:[2,3,0,1] row_mask:0xf bank_mask:0xf
	v_mov_b32_e32 v65, v52
	v_mov_b32_e32 v62, v52
	v_mov_b32_e32 v63, v52
	v_mov_b32_e32 v78, v52
	s_waitcnt lgkmcnt(0)
	v_max_f32_e32 v9, v9, v9
	v_max_f32_e32 v6, v6, v9
	s_nop 1
	v_mov_b32_dpp v9, v6 quad_perm:[1,0,3,2] row_mask:0xf bank_mask:0xf
	v_mov_b32_e32 v79, v52
	v_mov_b32_e32 v56, v52
	v_mov_b32_e32 v57, v52
	v_mov_b32_e32 v60, v52
	s_waitcnt lgkmcnt(0)
	v_max_f32_e32 v9, v9, v9
	v_max_f32_e32 v6, v6, v9
	v_sub_f32_e32 v2, v2, v6
	v_sub_f32_e32 v3, v3, v6
	v_mul_f32_e32 v2, 0x3fb8aa3b, v2
	v_sub_f32_e32 v4, v4, v6
	v_mul_f32_e32 v3, 0x3fb8aa3b, v3
	v_exp_f32_e32 v11, v2
	v_sub_f32_e32 v5, v5, v6
	v_mul_f32_e32 v4, 0x3fb8aa3b, v4
	v_exp_f32_e32 v12, v3
	v_mul_f32_e32 v5, 0x3fb8aa3b, v5
	v_exp_f32_e32 v13, v4
	v_exp_f32_e32 v14, v5
	v_add_f32_e32 v2, 0, v11
	v_add_f32_e32 v2, v12, v2
	v_add_f32_e32 v2, v13, v2
	v_add_f32_e32 v2, v14, v2
	ds_bpermute_b32 v3, v7, v2
	v_or_b32_e32 v4, 2, v72
	v_mov_b32_e32 v61, v52
	v_mov_b32_e32 v54, v52
	v_mov_b32_e32 v55, v52
	s_waitcnt lgkmcnt(0)
	v_add_f32_e32 v2, v2, v3
	ds_bpermute_b32 v3, v8, v2
	v_mov_b32_e32 v58, v52
	v_mov_b32_e32 v59, v52
	s_waitcnt lgkmcnt(0)
	v_add_f32_e32 v3, v2, v3
	s_nop 1
	v_mov_b32_dpp v5, v3 row_ror:8 row_mask:0xf bank_mask:0xf
	v_or_b32_e32 v2, 1, v72
	v_ashrrev_i32_e32 v73, 31, v72
	v_lshlrev_b64 v[36:37], 13, v[72:73]
	v_mov_b32_e32 v73, v52
	s_waitcnt lgkmcnt(0)
	v_add_f32_e32 v6, v3, v5
	s_nop 1
	v_mov_b32_dpp v194, v6 row_shr:4 row_mask:0xf bank_mask:0xa
	s_nop 0
	v_mov_b32_dpp v194, v6 row_shl:4 row_mask:0xf bank_mask:0x5
	v_mov_b32_e32 v7, v194
	v_ashrrev_i32_e32 v3, 31, v2
	v_ashrrev_i32_e32 v5, 31, v4
	v_lshlrev_b64 v[2:3], 13, v[2:3]
	v_lshlrev_b64 v[4:5], 13, v[4:5]
	s_waitcnt lgkmcnt(0)
	v_add_f32_e32 v15, v6, v7
	s_nop 1
	v_mov_b32_dpp v16, v15 quad_perm:[2,3,0,1] row_mask:0xf bank_mask:0xf
	v_lshl_add_u64 v[6:7], s[4:5], 0, v[34:35]
	v_lshl_add_u64 v[8:9], v[6:7], 0, v[36:37]
	v_lshl_add_u64 v[2:3], v[6:7], 0, v[2:3]
	v_lshl_add_u64 v[4:5], v[6:7], 0, v[4:5]
	s_waitcnt lgkmcnt(0)
	v_add_f32_e32 v15, v15, v16
	s_nop 1
	v_mov_b32_dpp v16, v15 quad_perm:[1,0,3,2] row_mask:0xf bank_mask:0xf
	v_lshl_add_u64 v[8:9], v[8:9], 0, v[66:67]
	v_lshl_add_u64 v[2:3], v[2:3], 0, v[66:67]
	v_lshl_add_u64 v[4:5], v[4:5], 0, v[66:67]
	v_lshl_add_u64 v[36:37], s[18:19], 0, v[36:37]
	s_waitcnt lgkmcnt(0)
	v_add_f32_e32 v15, v15, v16
	v_div_scale_f32 v16, s[4:5], v15, v15, 1.0
	v_rcp_f32_e32 v17, v16
	v_div_scale_f32 v18, vcc, 1.0, v15, 1.0
	v_lshl_or_b32 v36, v75, 4, v36
	v_fma_f32 v19, -v16, v17, 1.0
	v_fmac_f32_e32 v17, v19, v17
	v_mul_f32_e32 v19, v18, v17
	v_fma_f32 v20, -v16, v19, v18
	v_fmac_f32_e32 v19, v20, v17
	v_fma_f32 v16, -v16, v19, v18
	v_div_fmas_f32 v16, v16, v17, v19
	v_div_fixup_f32 v15, v16, v15, 1.0
	v_mul_f32_e32 v11, v11, v15
	v_mul_f32_e32 v12, v12, v15
	v_mul_f32_e32 v13, v13, v15
	v_mul_f32_e32 v14, v14, v15
	ds_write2st64_b32 v10, v11, v12 offset0:32 offset1:36
	ds_write2st64_b32 v10, v13, v14 offset0:40 offset1:44
	s_waitcnt lgkmcnt(0)
	s_barrier
	global_load_dwordx4 v[26:29], v[8:9], off nt
	global_load_dwordx4 v[30:33], v[8:9], off offset:1024 nt
	global_load_dwordx4 v[18:21], v[2:3], off nt
	global_load_dwordx4 v[22:25], v[2:3], off offset:1024 nt
	global_load_dwordx4 v[10:13], v[4:5], off nt
	global_load_dwordx4 v[14:17], v[4:5], off offset:1024 nt
	v_or_b32_e32 v2, 3, v72
	v_ashrrev_i32_e32 v3, 31, v2
	v_lshlrev_b64 v[2:3], 13, v[2:3]
	v_lshl_add_u64 v[2:3], v[6:7], 0, v[2:3]
	v_lshl_add_u64 v[38:39], v[2:3], 0, v[66:67]
	global_load_dwordx4 v[2:5], v[38:39], off nt
	global_load_dwordx4 v[6:9], v[38:39], off offset:1024 nt
	v_lshl_add_u64 v[34:35], v[36:37], 0, v[34:35]
	v_lshlrev_b32_e32 v66, 2, v75
	v_lshl_add_u64 v[50:51], s[10:11], 0, v[34:35]
	s_mov_b64 s[4:5], 0
	v_mov_b32_e32 v75, v52
	v_mov_b32_e32 v72, v52
	v_mov_b32_e32 v82, v52
	v_mov_b32_e32 v80, v52
	v_mov_b32_e32 v81, v52
